# modulation GEMV items of layers 1..3 moved from phase 0 to the spare workgroups of the previous layer's ffn2 phase; phase-0 weight-copy tiles only on workgroups without a modulation item
# baseline (speedup 1.0000x reference)
.LBB0_148:
	s_mov_b64 s[22:23], 0x400
	s_movk_i32 s39, 0x1000
	s_mov_b64 s[24:25], s[4:5]
	s_mov_b64 s[20:21], s[6:7]
	s_cbranch_execz .LBB0_144
	s_branch .LBB0_145
.Lp0_call:
	s_branch .Ltramp_678
.Lp0_resume:
.LBB0_149:
	s_mov_b64 s[4:5], 0

.Ltramp_678:
	s_branch .LBB0_678
.Lp0_ret_far:
	s_branch .Lp0_resume

.LBB0_678:
	v_readfirstlane_b32 s0, v160
	s_lshr_b32 s4, s0, 8
	s_add_i32 s14, s4, s90
	s_cmp_eq_u32 s76, 0
	s_cbranch_scc1 .Lp0_first
	v_readlane_b32 s0, v252, 0
	s_sub_i32 s0, s0, 0xa0
	s_lshl_b32 s0, s0, 1
	s_add_i32 s0, s0, s4
	v_readlane_b32 s1, v254, 34
	s_add_i32 s1, s1, 1
	s_mul_i32 s1, s1, 0x60
	s_add_i32 s14, s1, s0
	s_cmpk_lt_u32 s0, 0x60
	s_cselect_b32 s14, s14, 0x3e8
	s_branch .Lp0_cont
.Lp0_first:
	s_add_i32 s0, s14, 0xffffffa0
	s_cmpk_lt_u32 s0, 0x120
	s_cselect_b32 s14, 0x3e8, s14
.Lp0_cont:
	s_cmpk_lt_i32 s14, 0x19a
	s_mov_b64 s[0:1], -1
	s_cbranch_scc1 .LBB0_680
	s_load_dword s20, s[78:79], 0x0
	s_mov_b64 s[0:1], 0

.LBB0_722:
	s_waitcnt lgkmcnt(0)
	s_cmp_lg_u32 s76, 0
	s_cbranch_scc1 .Lp0_ret_far
	s_abs_i32 s0, s20
	v_cvt_f32_u32_e32 v0, s0
	s_sub_i32 s4, 0, s0
	v_readfirstlane_b32 s1, v160
	v_rcp_iflag_f32_e32 v0, v0
	s_nop 0
	v_mul_f32_e32 v0, 0x4f7ffffe, v0
	v_cvt_u32_f32_e32 v0, v0
	s_nop 0
	v_readfirstlane_b32 s5, v0
	s_mul_i32 s4, s4, s5
	s_mul_hi_u32 s4, s5, s4
	s_add_i32 s5, s5, s4
	s_mul_hi_u32 s4, s5, 0xc3
	s_mul_i32 s4, s4, s0
	s_sub_i32 s4, 0xc3, s4
	s_sub_i32 s6, s4, s0
	s_cmp_ge_u32 s4, s0
	s_cselect_b32 s4, s6, s4
	s_sub_i32 s6, s4, s0
	s_cmp_ge_u32 s4, s0
	s_cselect_b32 s4, s6, s4
	v_readlane_b32 s6, v252, 0
	s_add_i32 s6, s20, s6
	s_sub_i32 s4, s6, s4
	s_ashr_i32 s6, s4, 31
	s_abs_i32 s4, s4
	s_mul_hi_u32 s5, s4, s5
	s_mul_i32 s5, s5, s0
	s_sub_i32 s4, s4, s5
	s_sub_i32 s5, s4, s0
	s_cmp_ge_u32 s4, s0
	s_cselect_b32 s4, s5, s4
	s_sub_i32 s5, s4, s0
	s_cmp_ge_u32 s4, s0
	s_cselect_b32 s0, s5, s4
	s_xor_b32 s0, s0, s6
	s_sub_i32 s0, s0, s6
	s_lshr_b32 s10, s1, 8
	s_lshl_b32 s0, s0, 1
	s_add_i32 s21, s10, s0
	v_readlane_b32 s0, v252, 0
	s_sub_i32 s0, s0, 48
	s_lshl_b32 s21, s0, 1
	s_add_i32 s21, s21, s10
	s_cmp_lt_i32 s0, 0
	s_cselect_b32 s21, 0x7000, s21
	s_cmpk_gt_i32 s21, 0xc9f
	s_cbranch_scc1 .LBB0_749
	s_cmpk_gt_i32 s21, 0x39f
	s_cbranch_scc0 .LBB0_728
	s_cmpk_gt_u32 s21, 0x49f
	s_cbranch_scc0 .LBB0_729
	s_cmpk_gt_u32 s21, 0x89f
	s_cbranch_scc0 .LBB0_827
	s_add_i32 s4, s21, 0xfffff760
	v_readlane_b32 s56, v254, 14
	s_add_u32 s0, s84, 0x4600000
	v_readlane_b32 s68, v254, 26
	v_readlane_b32 s69, v254, 27
	s_addc_u32 s1, s85, 0
	s_lshr_b32 s22, s4, 4
	s_and_b32 s23, s21, 15
	v_readlane_b32 s57, v254, 15
	v_readlane_b32 s58, v254, 16
	v_readlane_b32 s59, v254, 17
	v_readlane_b32 s60, v254, 18
	v_readlane_b32 s61, v254, 19
	v_readlane_b32 s62, v254, 20
	v_readlane_b32 s63, v254, 21
	v_readlane_b32 s64, v254, 22
	v_readlane_b32 s65, v254, 23
	v_readlane_b32 s66, v254, 24
	v_readlane_b32 s67, v254, 25
	v_readlane_b32 s70, v254, 28
	v_readlane_b32 s71, v254, 29
	s_mov_b64 s[4:5], s[68:69]
	s_cbranch_execz .LBB0_828
	s_mov_b64 s[6:7], 0x400
	s_movk_i32 s24, 0x1000
	s_cbranch_execz .LBB0_730
	s_branch .LBB0_731

.LBB0_733:
	v_mov_b32 v0, 0
	s_movk_i32 s26, 0x1a0
	v_add_u32_sdwa v2, v0, v160 dst_sel:DWORD dst_unused:UNUSED_PAD src0_sel:DWORD src1_sel:BYTE_0
	v_ashrrev_i32_e32 v0, 4, v2
	v_lshl_add_u32 v10, s22, 6, v0
	v_add_u32_e32 v0, 48, v10
	v_add_u32_e32 v8, 16, v10
	v_ashrrev_i32_e32 v1, 31, v0
	v_lshlrev_b32_e32 v2, 4, v2
	v_ashrrev_i32_e32 v9, 31, v8
	v_mul_lo_u32 v3, s6, v1
	v_mul_lo_u32 v4, s7, v0
	v_mad_u64_u32 v[0:1], s[8:9], s6, v0, 0
	v_and_b32_e32 v128, 0xf0, v2
	v_add_u32_e32 v2, 32, v10
	v_mul_lo_u32 v11, s6, v9
	v_mul_lo_u32 v12, s7, v8
	v_mad_u64_u32 v[8:9], s[12:13], s6, v8, 0
	v_add3_u32 v1, v1, v3, v4
	v_ashrrev_i32_e32 v3, 31, v2
	v_add3_u32 v9, v9, v11, v12
	v_ashrrev_i32_e32 v11, 31, v10
	s_lshl_b32 s8, s23, 6
	v_mul_lo_u32 v4, s6, v3
	v_mul_lo_u32 v5, s7, v2
	v_mad_u64_u32 v[2:3], s[12:13], s6, v2, 0
	v_mul_lo_u32 v12, s6, v11
	v_mul_lo_u32 v13, s7, v10
	v_mad_u64_u32 v[10:11], s[6:7], s6, v10, 0
	s_ashr_i32 s9, s8, 31
	v_add3_u32 v3, v3, v4, v5
	v_add3_u32 v11, v11, v12, v13
	v_lshl_add_u64 v[0:1], v[0:1], 2, s[4:5]
	s_lshl_b64 s[8:9], s[8:9], 2
	v_lshl_add_u64 v[2:3], v[2:3], 2, s[4:5]
	v_lshl_add_u64 v[8:9], v[8:9], 2, s[4:5]
	v_lshl_add_u64 v[10:11], v[10:11], 2, s[4:5]
	v_lshl_add_u64 v[0:1], v[0:1], 0, s[8:9]
	v_lshl_add_u64 v[2:3], v[2:3], 0, s[8:9]
	v_lshl_add_u64 v[8:9], v[8:9], 0, s[8:9]
	v_lshl_add_u64 v[10:11], v[10:11], 0, s[8:9]
	v_lshl_add_u64 v[0:1], v[0:1], 0, v[128:129]
	v_lshl_add_u64 v[4:5], v[2:3], 0, v[128:129]
	v_lshl_add_u64 v[8:9], v[8:9], 0, v[128:129]
	v_lshl_add_u64 v[12:13], v[10:11], 0, v[128:129]
	global_load_dwordx4 v[0:3], v[0:1], off nt
	s_nop 0
	global_load_dwordx4 v[4:7], v[4:5], off nt
	s_nop 0
	global_load_dwordx4 v[8:11], v[8:9], off nt
	s_nop 0
	global_load_dwordx4 v[12:15], v[12:13], off nt
	s_lshl_b32 s4, s10, 16
	s_add_i32 s25, s4, 0
	s_add_u32 s4, s84, 0x4600000
	s_addc_u32 s5, s85, 0
	s_add_u32 s6, s84, 0x2600000
	s_addc_u32 s7, s85, 0
	s_add_u32 s8, s84, 0x1e00000
	s_addc_u32 s9, s85, 0
	s_mov_b32 s28, s23
	s_mov_b32 s27, s22
	s_mov_b32 s29, s24
	s_mov_b64 s[12:13], s[0:1]
	s_branch .LBB0_737
